# P13: next unit's filter row prefetched during the current unit's last pair (on top of sample prefetch)
# speedup vs baseline: 1.0014x; 1.0014x over previous
; #define AIN(i) ((const float*)ldarg(i))
; #define G lgrid()
; #define bx lbid()
; #define IN(k) (ldint(248) <= (k) && (k) < ldint(252) && !((SKIP_MASK >> (k)) & 1u))
; __global__ void __launch_bounds__(NTHR, 2) mega_fwd(Args a_unused) {
;     ...
;       if (IN(13)) {
;         float2* A = (float2*)lds; float2* Hb = (float2*)(lds + 69632); float* wsm = (float*)(lds + 139264); bf16* UT = (bf16*)AOUT;
;         const float* w3 = AIN(22); const float* skip = AIN(23);
; #pragma unroll 1
;         for (int u = bx; u < 4096; u += G) {
;           const int gsel = u < 2048 ? 1 : 0, c = u & 2047;
.LBB0_640:
	s_mov_b64 s[8:9], s[0:1]
	s_load_dword s5, s[8:9], 0xf8
	s_waitcnt lgkmcnt(0)
	s_cmp_gt_i32 s5, 13
	s_cbranch_scc1 .LBB0_693
	s_mov_b64 s[8:9], s[0:1]
	s_load_dword s5, s[8:9], 0xfc
	s_waitcnt lgkmcnt(0)
	s_cmp_lt_i32 s5, 14
	s_cbranch_scc1 .LBB0_693
	s_mov_b64 s[8:9], s[0:1]
	s_mov_b64 s[10:11], s[0:1]
	s_mov_b64 s[10:11], s[0:1]
	s_mov_b32 s5, s54
	s_cmpk_gt_i32 s5, 0xfff
	s_cbranch_scc1 .LBB0_692
	s_mov_b32 s24, 0
	s_load_dwordx2 s[8:9], s[8:9], 0xe8
	s_branch .LBB0_645

; #define tid ltid()
; __global__ void __launch_bounds__(NTHR, 2) mega_fwd(Args a_unused) {
;     ...
;           const int L = gsel ? 4096 : 2048, N = 2 * L;
;           const float* hd = (const float*)(ws + (gsel ? WS_HDN_S : WS_HDN_P));
;           __syncthreads();
;           { const float* frow = (const float*)((const char*)AOUT + 192 * MiB) + (gsel ? (size_t)c * 8192 : (size_t)2048 * 8192 + (size_t)c * 4096);
;             for (int n = tid; n < N; n += NTHR) Hb[PIDX(n)] = make_float2(frow[n], 0.f); }
;           __syncthreads();
.Lpf_unit_half:
	s_nop 0
	v_cmp_gt_i32_e32 vcc, s18, v0
	s_and_saveexec_b64 s[12:13], vcc
	s_cbranch_execz .LBB0_648
	s_load_dwordx2 s[14:15], s[14:15], 0xe8
	s_lshl_b32 s20, s17, 12
	s_lshl_b32 s19, s17, 13
	s_or_b32 s22, s20, 0x1000000
	s_and_b64 s[20:21], s[42:43], exec
	s_cselect_b32 s19, s19, s22
	s_lshl_b32 s19, s19, 2
	s_waitcnt lgkmcnt(0)
	s_add_u32 s14, s14, s19
	v_ashrrev_i32_e32 v1, 31, v0
	s_addc_u32 s15, s15, 0
	v_lshl_add_u64 v[2:3], v[0:1], 2, s[14:15]
	s_mov_b64 s[14:15], 0xc000000
	v_lshl_add_u64 v[2:3], v[2:3], 0, s[14:15]
	v_lshl_add_u32 v1, v0, 3, s52
	v_ashrrev_i32_e32 v4, 4, v0
	v_lshl_add_u32 v4, v4, 3, v1
	s_mov_b64 s[20:21], 0x1000
	s_cmp_lg_u32 s24, 0
	s_cbranch_scc1 .Lfl_have
	v_mov_b32_e32 v151, 0
	v_mov_b32_e32 v153, 0
	v_mov_b32_e32 v155, 0
	v_mov_b32_e32 v157, 0
	v_mov_b32_e32 v159, 0
	v_mov_b32_e32 v161, 0
	v_mov_b32_e32 v163, 0
	v_mov_b32_e32 v165, 0
	v_mov_b32_e32 v167, 0
	v_mov_b32_e32 v169, 0
	v_mov_b32_e32 v171, 0
	v_mov_b32_e32 v173, 0
	v_mov_b32_e32 v175, 0
	v_mov_b32_e32 v177, 0
	v_mov_b32_e32 v179, 0
	v_mov_b32_e32 v181, 0
	global_load_dword v150, v[2:3], off
	global_load_dword v152, v[2:3], off offset:2048
	v_lshl_add_u64 v[2:3], v[2:3], 0, s[20:21]
	global_load_dword v154, v[2:3], off
	global_load_dword v156, v[2:3], off offset:2048
	v_lshl_add_u64 v[2:3], v[2:3], 0, s[20:21]
	global_load_dword v158, v[2:3], off
	global_load_dword v160, v[2:3], off offset:2048
	v_lshl_add_u64 v[2:3], v[2:3], 0, s[20:21]
	global_load_dword v162, v[2:3], off
	global_load_dword v164, v[2:3], off offset:2048
	v_lshl_add_u64 v[2:3], v[2:3], 0, s[20:21]
	s_cmp_lg_u32 s18, 0x2000
	s_cbranch_scc1 .Lfload_half
	global_load_dword v166, v[2:3], off
	global_load_dword v168, v[2:3], off offset:2048
	v_lshl_add_u64 v[2:3], v[2:3], 0, s[20:21]
	global_load_dword v170, v[2:3], off
	global_load_dword v172, v[2:3], off offset:2048
	v_lshl_add_u64 v[2:3], v[2:3], 0, s[20:21]
	global_load_dword v174, v[2:3], off
	global_load_dword v176, v[2:3], off offset:2048
	v_lshl_add_u64 v[2:3], v[2:3], 0, s[20:21]
	global_load_dword v178, v[2:3], off
	global_load_dword v180, v[2:3], off offset:2048
	s_waitcnt vmcnt(8)
	ds_write_b64 v4, v[150:151] offset:0
	ds_write_b64 v4, v[152:153] offset:4352
	ds_write_b64 v4, v[154:155] offset:8704
	ds_write_b64 v4, v[156:157] offset:13056
	ds_write_b64 v4, v[158:159] offset:17408
	ds_write_b64 v4, v[160:161] offset:21760
	ds_write_b64 v4, v[162:163] offset:26112
	ds_write_b64 v4, v[164:165] offset:30464
	s_waitcnt vmcnt(0)
	ds_write_b64 v4, v[166:167] offset:34816
	ds_write_b64 v4, v[168:169] offset:39168
	ds_write_b64 v4, v[170:171] offset:43520
	ds_write_b64 v4, v[172:173] offset:47872
	ds_write_b64 v4, v[174:175] offset:52224
	ds_write_b64 v4, v[176:177] offset:56576
	ds_write_b64 v4, v[178:179] offset:60928
	ds_write_b64 v4, v[180:181] offset:65280
	s_branch .LBB0_648
.Lfload_half:
	s_waitcnt vmcnt(0)
	ds_write_b64 v4, v[150:151] offset:0
	ds_write_b64 v4, v[152:153] offset:4352
	ds_write_b64 v4, v[154:155] offset:8704
	ds_write_b64 v4, v[156:157] offset:13056
	ds_write_b64 v4, v[158:159] offset:17408
	ds_write_b64 v4, v[160:161] offset:21760
	ds_write_b64 v4, v[162:163] offset:26112
	ds_write_b64 v4, v[164:165] offset:30464
	s_branch .LBB0_648
.Lfl_have:
	s_cmp_lg_u32 s18, 0x2000
	s_cbranch_scc1 .Lfl_have_half
	ds_write_b64 v4, v[150:151] offset:0
	ds_write_b64 v4, v[152:153] offset:4352
	ds_write_b64 v4, v[154:155] offset:8704
	ds_write_b64 v4, v[156:157] offset:13056
	ds_write_b64 v4, v[158:159] offset:17408
	ds_write_b64 v4, v[160:161] offset:21760
	ds_write_b64 v4, v[162:163] offset:26112
	ds_write_b64 v4, v[164:165] offset:30464
	ds_write_b64 v4, v[166:167] offset:34816
	ds_write_b64 v4, v[168:169] offset:39168
	ds_write_b64 v4, v[170:171] offset:43520
	ds_write_b64 v4, v[172:173] offset:47872
	ds_write_b64 v4, v[174:175] offset:52224
	ds_write_b64 v4, v[176:177] offset:56576
	ds_write_b64 v4, v[178:179] offset:60928
	ds_write_b64 v4, v[180:181] offset:65280
	s_branch .LBB0_648
.Lfl_have_half:
	ds_write_b64 v4, v[150:151] offset:0
	ds_write_b64 v4, v[152:153] offset:4352
	ds_write_b64 v4, v[154:155] offset:8704
	ds_write_b64 v4, v[156:157] offset:13056
	ds_write_b64 v4, v[158:159] offset:17408
	ds_write_b64 v4, v[160:161] offset:21760
	ds_write_b64 v4, v[162:163] offset:26112
	ds_write_b64 v4, v[164:165] offset:30464

; #define tid ltid()
; #define G lgrid()
; #define bx lbid()
; __global__ void __launch_bounds__(NTHR, 2) mega_fwd(Args a_unused) {
;     ...
;         for (int u = bx; u < 4096; u += G) {
;           const int gsel = u < 2048 ? 1 : 0, c = u & 2047;
;           const int L = gsel ? 4096 : 2048, N = 2 * L;
;           const float* hd = (const float*)(ws + (gsel ? WS_HDN_S : WS_HDN_P));
;           __syncthreads();
;           { const float* frow = (const float*)((const char*)AOUT + 192 * MiB) + (gsel ? (size_t)c * 8192 : (size_t)2048 * 8192 + (size_t)c * 4096);
;             for (int n = tid; n < N; n += NTHR) Hb[PIDX(n)] = make_float2(frow[n], 0.f); }
.Lpf_skip_a:
	s_cmp_lg_u32 s18, 3
	s_cbranch_scc1 .Lflpf_done_a
	s_mov_b32 s24, 0
	s_add_i32 s57, s5, s56
	s_cmpk_gt_i32 s57, 0xfff
	s_cbranch_scc1 .Lflpf_done_a
	s_mov_b32 s24, 1
	s_and_b32 s26, s57, 0x7ff
	s_lshl_b32 s29, s26, 12
	s_lshl_b32 s26, s26, 13
	s_or_b32 s29, s29, 0x1000000
	s_cmpk_lt_i32 s57, 0x800
	s_cselect_b32 s26, s26, s29
	s_lshl_b32 s26, s26, 2
	s_add_u32 s80, s8, s26
	s_addc_u32 s81, s9, 0
	s_add_u32 s80, s80, 0xc000000
	s_addc_u32 s81, s81, 0
	v_lshlrev_b32_e32 v234, 2, v208
	v_mov_b32_e32 v235, 0
	v_lshl_add_u64 v[234:235], s[80:81], 0, v[234:235]
	s_mov_b64 s[96:97], 0x1000
	global_load_dword v150, v[234:235], off
	global_load_dword v152, v[234:235], off offset:2048
	v_lshl_add_u64 v[234:235], v[234:235], 0, s[96:97]
	global_load_dword v154, v[234:235], off
	global_load_dword v156, v[234:235], off offset:2048
	v_lshl_add_u64 v[234:235], v[234:235], 0, s[96:97]
	global_load_dword v158, v[234:235], off
	global_load_dword v160, v[234:235], off offset:2048
	v_lshl_add_u64 v[234:235], v[234:235], 0, s[96:97]
	global_load_dword v162, v[234:235], off
	global_load_dword v164, v[234:235], off offset:2048
	v_lshl_add_u64 v[234:235], v[234:235], 0, s[96:97]
	s_cmpk_lt_i32 s57, 0x800
	s_cbranch_scc0 .Lflpf_done_a
	global_load_dword v166, v[234:235], off
	global_load_dword v168, v[234:235], off offset:2048
	v_lshl_add_u64 v[234:235], v[234:235], 0, s[96:97]
	global_load_dword v170, v[234:235], off
	global_load_dword v172, v[234:235], off offset:2048
	v_lshl_add_u64 v[234:235], v[234:235], 0, s[96:97]
	global_load_dword v174, v[234:235], off
	global_load_dword v176, v[234:235], off offset:2048
	v_lshl_add_u64 v[234:235], v[234:235], 0, s[96:97]
	global_load_dword v178, v[234:235], off
	global_load_dword v180, v[234:235], off offset:2048
